# fused norm_rows after the output projection rewritten by hand: parameters resident in VGPRs, all loads of a row together, next row prefetched, counted vmcnt (was store/3 loads/vmcnt(0) x8 per row)
# baseline (speedup 1.0000x reference)
; __device__ __forceinline__ unsigned pk2(float lo, float hi) { return f2bf(lo) | (f2bf(hi) << 16); }
; __device__ __forceinline__ void norm_rows(const float* X, const float* nw, const float* md, u16* H, int row0, int nrows, int wave, int lane) {
;     for (int row = row0 + wave; row < row0 + nrows; row += 8) {
;         const float4* xr = (const float4*)(X + (size_t)row * DM) + lane; float4 v[8]; float ss = 0.f;
; #pragma unroll
;         for (int j = 0; j < 8; ++j) { v[j] = xr[64 * j]; ss += v[j].x * v[j].x + v[j].y * v[j].y + v[j].z * v[j].z + v[j].w * v[j].w; }
;         const float r = rsqrtf(wave_sum(ss) * (1.f / DM) + EPS);
;         uint2* hp = (uint2*)(H + (size_t)row * DM) + lane;
; #pragma unroll
;         for (int j = 0; j < 8; ++j) { const int col = 4 * (lane + 64 * j); const float4 w4 = *(const float4*)(nw + col), sc = *(const float4*)(md + 2048 + col), sh = *(const float4*)(md + col);
;             uint2 o; o.x = pk2(v[j].x * r * w4.x * (1.f + sc.x) + sh.x, v[j].y * r * w4.y * (1.f + sc.y) + sh.y);
;             o.y = pk2(v[j].z * r * w4.z * (1.f + sc.z) + sh.z, v[j].w * r * w4.w * (1.f + sc.w) + sh.w); hp[64 * j] = o; } }
; __global__ void __launch_bounds__(512, 2) mega(Params p) {
;     ...
;           if (l < 3) { const float* mod1 = MOD + (size_t)(l + 1) * 2 * 6144; const float* nw1 = p.in[6] + (size_t)(l + 1) * DM;
;               norm_rows(X, nw1, mod1, H, pm * 256 + pn * 32, 32, wave, lane);
.LBB0_1294:
	s_andn2_b64 vcc, exec, s[6:7]
	s_cbranch_vccnz .LBB0_1313
	v_readlane_b32 s0, v254, 59
	v_readlane_b32 s1, v254, 60
	s_add_i32 s84, s0, 1
	s_mul_i32 s1, s84, 0xc000
	v_readlane_b32 s6, v251, 36
	s_mul_hi_u32 s0, s84, 0xc000
	v_readlane_b32 s7, v251, 37
	s_add_u32 s34, s6, s1
	v_readlane_b32 s40, v251, 2
	s_addc_u32 s35, s7, s0
	s_lshl_b64 s[0:1], s[84:85], 13
	v_readlane_b32 s52, v251, 14
	v_readlane_b32 s53, v251, 15
	s_add_u32 s0, s52, s0
	v_readlane_b32 s41, v251, 3
	v_readlane_b32 s48, v251, 10
	v_readlane_b32 s49, v251, 11
	v_readlane_b32 s50, v251, 12
	v_readlane_b32 s51, v251, 13
	s_addc_u32 s1, s53, s1
	v_cmp_gt_i32_e32 vcc, 32, v71
	v_readlane_b32 s42, v251, 4
	v_readlane_b32 s43, v251, 5
	v_readlane_b32 s44, v251, 6
	v_readlane_b32 s45, v251, 7
	v_readlane_b32 s46, v251, 8
	v_readlane_b32 s47, v251, 9
	v_readlane_b32 s54, v251, 16
	v_readlane_b32 s55, v251, 17
	s_and_saveexec_b64 s[40:41], vcc
	v_readlane_b32 s44, v254, 16
	v_readlane_b32 s11, v253, 25
	s_mov_b32 s12, 0xa001000
	s_mov_b32 s13, 0xe200000
	s_mov_b64 s[16:17], 0x10000
	s_mov_b64 s[18:19], 0x8000
	v_readlane_b32 s48, v254, 20
	v_readlane_b32 s49, v254, 21
	v_readlane_b32 s50, v254, 22
	v_readlane_b32 s51, v254, 23
	v_readlane_b32 s45, v254, 17
	v_readlane_b32 s46, v254, 18
	v_readlane_b32 s47, v254, 19
	s_cbranch_execz .LBB0_1298
	v_cmp_lt_i32_e32 vcc, v178, v172
	s_add_u32 s6, s34, 0x2000
	v_lshlrev_b32_e32 v164, 4, v70
	v_cndmask_b32_e32 v0, v171, v178, vcc
	v_cmp_lt_i32_e32 vcc, v177, v172
	v_lshlrev_b32_e32 v65, 2, v0
	s_addc_u32 s7, s35, 0
	v_cndmask_b32_e32 v0, v171, v177, vcc
	v_cmp_lt_i32_e32 vcc, v176, v172
	v_lshlrev_b32_e32 v90, 2, v0
	v_mov_b32_e32 v1, v165
	v_cndmask_b32_e32 v0, v171, v176, vcc
	v_lshlrev_b32_e32 v91, 2, v0
	v_xor_b32_e32 v0, 8, v171
	v_cmp_lt_i32_e32 vcc, v0, v172
	v_lshl_add_u64 v[26:27], s[6:7], 0, v[164:165]
	s_mov_b64 s[44:45], s[48:49]
	v_cndmask_b32_e32 v0, v171, v0, vcc
	v_lshlrev_b32_e32 v92, 2, v0
	v_xor_b32_e32 v0, 16, v171
	v_cmp_lt_i32_e32 vcc, v0, v172
	s_mov_b64 s[46:47], s[50:51]
	v_lshl_add_u64 v[24:25], s[0:1], 0, v[164:165]
	v_cndmask_b32_e32 v0, v171, v0, vcc
	v_lshlrev_b32_e32 v93, 2, v0
	v_xor_b32_e32 v0, 32, v171
	v_cmp_lt_i32_e32 vcc, v0, v172
	v_lshl_add_u64 v[28:29], s[34:35], 0, v[164:165]
	s_mov_b64 s[42:43], 0
	v_cndmask_b32_e32 v0, v171, v0, vcc
	v_lshlrev_b32_e32 v94, 2, v0
	v_or_b32_e32 v0, 0x400, v164
	v_lshl_add_u64 v[30:31], s[6:7], 0, v[0:1]
	v_or_b32_e32 v0, 0x800, v164
	v_lshl_add_u64 v[32:33], s[6:7], 0, v[0:1]
	v_or_b32_e32 v0, 0xc00, v164
	v_lshl_add_u64 v[34:35], s[6:7], 0, v[0:1]
	v_or_b32_e32 v0, 0x1000, v164
	v_lshl_add_u64 v[36:37], s[0:1], 0, v[0:1]
	v_lshl_add_u64 v[38:39], s[6:7], 0, v[0:1]
	v_lshl_add_u64 v[40:41], s[34:35], 0, v[0:1]
	v_or_b32_e32 v0, 0x1400, v164
	v_lshl_add_u64 v[42:43], s[0:1], 0, v[0:1]
	v_lshl_add_u64 v[44:45], s[6:7], 0, v[0:1]
	v_lshl_add_u64 v[46:47], s[34:35], 0, v[0:1]
	v_or_b32_e32 v0, 0x1800, v164
	v_lshl_add_u64 v[48:49], s[0:1], 0, v[0:1]
	v_lshl_add_u64 v[50:51], s[6:7], 0, v[0:1]
	v_lshl_add_u64 v[52:53], s[34:35], 0, v[0:1]
	v_or_b32_e32 v0, 0x1c00, v164
	v_lshl_add_u64 v[56:57], s[6:7], 0, v[0:1]
	v_readlane_b32 s6, v254, 33
	v_lshl_add_u64 v[54:55], s[0:1], 0, v[0:1]
	v_lshl_add_u64 v[58:59], s[34:35], 0, v[0:1]
	v_add_u32_e32 v95, s6, v71
	v_readlane_b32 s6, v254, 32
	s_nop 1
	v_add_u32_e32 v0, s6, v71
	v_ashrrev_i32_e32 v1, 31, v0
	v_lshlrev_b64 v[60:61], 13, v[0:1]
	v_lshlrev_b64 v[62:63], 12, v[0:1]
	v_or_b32_e32 v60, v60, v164
	v_lshl_or_b32 v62, v70, 3, v62
	global_load_dwordx4 v[182:185], v[24:25], off
	global_load_dwordx4 v[186:189], v[24:25], off offset:1024
	global_load_dwordx4 v[190:193], v[24:25], off offset:2048
	global_load_dwordx4 v[194:197], v[24:25], off offset:3072
	global_load_dwordx4 v[198:201], v[36:37], off
	global_load_dwordx4 v[202:205], v[42:43], off
	global_load_dwordx4 v[206:209], v[48:49], off
	global_load_dwordx4 v[210:213], v[54:55], off
	global_load_dwordx4 v[214:217], v[26:27], off
	global_load_dwordx4 v[218:221], v[30:31], off
	global_load_dwordx4 v[222:225], v[32:33], off
	global_load_dwordx4 v[226:229], v[34:35], off
	global_load_dwordx4 v[230:233], v[38:39], off
	global_load_dwordx4 v[234:237], v[44:45], off
	global_load_dwordx4 v[238:241], v[50:51], off
	global_load_dwordx4 v[242:245], v[56:57], off
	global_load_dwordx4 v[0:3], v[28:29], off
	global_load_dwordx4 v[4:7], v[28:29], off offset:1024
	global_load_dwordx4 v[8:11], v[28:29], off offset:2048
	global_load_dwordx4 v[12:15], v[28:29], off offset:3072
	global_load_dwordx4 v[16:19], v[40:41], off
	global_load_dwordx4 v[20:23], v[46:47], off
	global_load_dwordx4 v[66:69], v[52:53], off
	global_load_dwordx4 v[70:73], v[58:59], off
	s_mov_b32 s101, 0x7060302
	v_lshl_add_u64 v[74:75], s[46:47], 0, v[60:61]
	v_add_co_u32_e32 v76, vcc, s12, v74
	s_nop 1
	v_addc_co_u32_e32 v77, vcc, 0, v75, vcc
	v_add_co_u32_e32 v74, vcc, 0xa000000, v74
	s_nop 1
	v_addc_co_u32_e32 v75, vcc, 0, v75, vcc
	global_load_dwordx4 v[100:103], v[74:75], off
	global_load_dwordx4 v[104:107], v[74:75], off offset:1024
	global_load_dwordx4 v[108:111], v[74:75], off offset:2048
	global_load_dwordx4 v[112:115], v[74:75], off offset:3072
	global_load_dwordx4 v[116:119], v[76:77], off
	global_load_dwordx4 v[120:123], v[76:77], off offset:1024
	global_load_dwordx4 v[124:127], v[76:77], off offset:2048
	global_load_dwordx4 v[128:131], v[76:77], off offset:3072
	v_lshl_add_u64 v[78:79], s[46:47], 0, v[62:63]
	v_add_co_u32_e32 v78, vcc, s13, v78
	s_nop 1
	v_addc_co_u32_e32 v79, vcc, 0, v79, vcc
	v_lshl_add_u64 v[60:61], v[60:61], 0, s[16:17]
	v_lshl_add_u64 v[62:63], v[62:63], 0, s[18:19]
	v_lshl_add_u64 v[74:75], s[46:47], 0, v[60:61]
	v_add_co_u32_e32 v76, vcc, s12, v74
	s_nop 1
	v_addc_co_u32_e32 v77, vcc, 0, v75, vcc
	v_add_co_u32_e32 v74, vcc, 0xa000000, v74
	s_nop 1
	v_addc_co_u32_e32 v75, vcc, 0, v75, vcc
	global_load_dwordx4 v[132:135], v[74:75], off
	global_load_dwordx4 v[136:139], v[74:75], off offset:1024
	global_load_dwordx4 v[140:143], v[74:75], off offset:2048
	global_load_dwordx4 v[144:147], v[74:75], off offset:3072
	global_load_dwordx4 v[148:151], v[76:77], off
	global_load_dwordx4 v[152:155], v[76:77], off offset:1024
	global_load_dwordx4 v[156:159], v[76:77], off offset:2048
	global_load_dwordx4 v[160:163], v[76:77], off offset:3072
	s_waitcnt vmcnt(8)
; __device__ __forceinline__ unsigned pk2(float lo, float hi) { return f2bf(lo) | (f2bf(hi) << 16); }
; __device__ __forceinline__ void norm_rows(const float* X, const float* nw, const float* md, u16* H, int row0, int nrows, int wave, int lane) {
;     for (int row = row0 + wave; row < row0 + nrows; row += 8) {
;         const float4* xr = (const float4*)(X + (size_t)row * DM) + lane; float4 v[8]; float ss = 0.f;
; #pragma unroll
;         for (int j = 0; j < 8; ++j) { v[j] = xr[64 * j]; ss += v[j].x * v[j].x + v[j].y * v[j].y + v[j].z * v[j].z + v[j].w * v[j].w; }
;         const float r = rsqrtf(wave_sum(ss) * (1.f / DM) + EPS);
;         uint2* hp = (uint2*)(H + (size_t)row * DM) + lane;
; #pragma unroll
;         for (int j = 0; j < 8; ++j) { const int col = 4 * (lane + 64 * j); const float4 w4 = *(const float4*)(nw + col), sc = *(const float4*)(md + 2048 + col), sh = *(const float4*)(md + col);
;             uint2 o; o.x = pk2(v[j].x * r * w4.x * (1.f + sc.x) + sh.x, v[j].y * r * w4.y * (1.f + sc.y) + sh.y);
;             o.y = pk2(v[j].z * r * w4.z * (1.f + sc.z) + sh.z, v[j].w * r * w4.w * (1.f + sc.w) + sh.w); hp[64 * j] = o; } }
	v_add_f32_e32 v214, 1.0, v214
	v_add_f32_e32 v215, 1.0, v215
	v_add_f32_e32 v216, 1.0, v216
	v_add_f32_e32 v217, 1.0, v217
	v_add_f32_e32 v218, 1.0, v218
	v_add_f32_e32 v219, 1.0, v219
	v_add_f32_e32 v220, 1.0, v220
	v_add_f32_e32 v221, 1.0, v221
	v_add_f32_e32 v222, 1.0, v222
	v_add_f32_e32 v223, 1.0, v223
	v_add_f32_e32 v224, 1.0, v224
	v_add_f32_e32 v225, 1.0, v225
	v_add_f32_e32 v226, 1.0, v226
	v_add_f32_e32 v227, 1.0, v227
	v_add_f32_e32 v228, 1.0, v228
	v_add_f32_e32 v229, 1.0, v229
	v_add_f32_e32 v230, 1.0, v230
	v_add_f32_e32 v231, 1.0, v231
	v_add_f32_e32 v232, 1.0, v232
	v_add_f32_e32 v233, 1.0, v233
	v_add_f32_e32 v234, 1.0, v234
	v_add_f32_e32 v235, 1.0, v235
	v_add_f32_e32 v236, 1.0, v236
	v_add_f32_e32 v237, 1.0, v237
	v_add_f32_e32 v238, 1.0, v238
	v_add_f32_e32 v239, 1.0, v239
	v_add_f32_e32 v240, 1.0, v240
	v_add_f32_e32 v241, 1.0, v241
	v_add_f32_e32 v242, 1.0, v242
	v_add_f32_e32 v243, 1.0, v243
	v_add_f32_e32 v244, 1.0, v244
	v_add_f32_e32 v245, 1.0, v245
	v_mul_f32_e32 v81, v101, v101
	v_fmac_f32_e32 v81, v100, v100
	v_fmac_f32_e32 v81, v102, v102
	v_fmac_f32_e32 v81, v103, v103
	v_mul_f32_e32 v80, v105, v105
	v_fmac_f32_e32 v80, v104, v104
	v_fmac_f32_e32 v80, v106, v106
	v_fmac_f32_e32 v80, v107, v107
	v_add_f32_e32 v81, v81, v80
	v_mul_f32_e32 v80, v109, v109
	v_fmac_f32_e32 v80, v108, v108
	v_fmac_f32_e32 v80, v110, v110
	v_fmac_f32_e32 v80, v111, v111
	v_add_f32_e32 v81, v81, v80
	v_mul_f32_e32 v80, v113, v113
	v_fmac_f32_e32 v80, v112, v112
	v_fmac_f32_e32 v80, v114, v114
	v_fmac_f32_e32 v80, v115, v115
	v_add_f32_e32 v81, v81, v80
	v_mul_f32_e32 v80, v117, v117
	v_fmac_f32_e32 v80, v116, v116
	v_fmac_f32_e32 v80, v118, v118
	v_fmac_f32_e32 v80, v119, v119
	v_add_f32_e32 v81, v81, v80
	v_mul_f32_e32 v80, v121, v121
	v_fmac_f32_e32 v80, v120, v120
	v_fmac_f32_e32 v80, v122, v122
	v_fmac_f32_e32 v80, v123, v123
	v_add_f32_e32 v81, v81, v80
	v_mul_f32_e32 v80, v125, v125
	v_fmac_f32_e32 v80, v124, v124
	v_fmac_f32_e32 v80, v126, v126
	v_fmac_f32_e32 v80, v127, v127
	v_add_f32_e32 v81, v81, v80
	v_mul_f32_e32 v80, v129, v129
	v_fmac_f32_e32 v80, v128, v128
	v_fmac_f32_e32 v80, v130, v130
	v_fmac_f32_e32 v80, v131, v131
	v_add_f32_e32 v81, v81, v80
	ds_bpermute_b32 v80, v65, v81
	s_waitcnt lgkmcnt(0)
	v_add_f32_e32 v81, v81, v80
	ds_bpermute_b32 v80, v90, v81
	s_waitcnt lgkmcnt(0)
	v_add_f32_e32 v81, v81, v80
	ds_bpermute_b32 v80, v91, v81
	s_waitcnt lgkmcnt(0)
	v_add_f32_e32 v81, v81, v80
	ds_bpermute_b32 v80, v92, v81
	s_waitcnt lgkmcnt(0)
	v_add_f32_e32 v81, v81, v80
	ds_bpermute_b32 v80, v93, v81
	s_waitcnt lgkmcnt(0)
	v_add_f32_e32 v81, v81, v80
	ds_bpermute_b32 v80, v94, v81
	s_waitcnt lgkmcnt(0)
	v_add_f32_e32 v81, v81, v80
	v_fmamk_f32 v81, v81, 0x3a000000, v179
	v_cmp_gt_f32_e32 vcc, s91, v81
	v_mul_f32_e32 v80, 0x4b800000, v81
	s_nop 0
	v_cndmask_b32_e32 v81, v81, v80, vcc
	v_rsq_f32_e32 v81, v81
	s_nop 0
	v_mul_f32_e32 v80, 0x45800000, v81
	v_cndmask_b32_e32 v82, v81, v80, vcc
	v_mul_f32_e32 v84, v100, v82
	v_mul_f32_e32 v85, v101, v82
	v_mul_f32_e32 v86, v102, v82
	v_mul_f32_e32 v87, v103, v82
	v_mul_f32_e32 v84, v182, v84
	v_mul_f32_e32 v85, v183, v85
	v_mul_f32_e32 v86, v184, v86
	v_mul_f32_e32 v87, v185, v87
	v_fma_f32 v84, v214, v84, v0
	v_fma_f32 v85, v215, v85, v1
	v_fma_f32 v86, v216, v86, v2
	v_fma_f32 v87, v217, v87, v3
	v_bfe_u32 v88, v84, 16, 1
	v_bfe_u32 v89, v85, 16, 1
	v_bfe_u32 v96, v86, 16, 1
	v_bfe_u32 v97, v87, 16, 1
	v_add3_u32 v84, v84, v88, s3
	v_add3_u32 v85, v85, v89, s3
	v_add3_u32 v86, v86, v96, s3
	v_add3_u32 v87, v87, v97, s3
	v_perm_b32 v98, v85, v84, s101
	v_perm_b32 v99, v87, v86, s101
	global_store_dwordx2 v[78:79], v[98:99], off
	v_mul_f32_e32 v84, v104, v82
	v_mul_f32_e32 v85, v105, v82
	v_mul_f32_e32 v86, v106, v82
	v_mul_f32_e32 v87, v107, v82
	v_mul_f32_e32 v84, v186, v84
	v_mul_f32_e32 v85, v187, v85
	v_mul_f32_e32 v86, v188, v86
	v_mul_f32_e32 v87, v189, v87
	v_fma_f32 v84, v218, v84, v4
	v_fma_f32 v85, v219, v85, v5
	v_fma_f32 v86, v220, v86, v6
	v_fma_f32 v87, v221, v87, v7
	v_bfe_u32 v88, v84, 16, 1
	v_bfe_u32 v89, v85, 16, 1
	v_bfe_u32 v96, v86, 16, 1
	v_bfe_u32 v97, v87, 16, 1
	v_add3_u32 v84, v84, v88, s3
	v_add3_u32 v85, v85, v89, s3
	v_add3_u32 v86, v86, v96, s3
	v_add3_u32 v87, v87, v97, s3
	v_perm_b32 v248, v85, v84, s101
	v_perm_b32 v249, v87, v86, s101
	global_store_dwordx2 v[78:79], v[248:249], off offset:512
	v_mul_f32_e32 v84, v108, v82
	v_mul_f32_e32 v85, v109, v82
	v_mul_f32_e32 v86, v110, v82
	v_mul_f32_e32 v87, v111, v82
	v_mul_f32_e32 v84, v190, v84
	v_mul_f32_e32 v85, v191, v85
	v_mul_f32_e32 v86, v192, v86
	v_mul_f32_e32 v87, v193, v87
	v_fma_f32 v84, v222, v84, v8
	v_fma_f32 v85, v223, v85, v9
	v_fma_f32 v86, v224, v86, v10
	v_fma_f32 v87, v225, v87, v11
	v_bfe_u32 v88, v84, 16, 1
	v_bfe_u32 v89, v85, 16, 1
	v_bfe_u32 v96, v86, 16, 1
	v_bfe_u32 v97, v87, 16, 1
	v_add3_u32 v84, v84, v88, s3
	v_add3_u32 v85, v85, v89, s3
	v_add3_u32 v86, v86, v96, s3
	v_add3_u32 v87, v87, v97, s3
	v_perm_b32 v98, v85, v84, s101
	v_perm_b32 v99, v87, v86, s101
	global_store_dwordx2 v[78:79], v[98:99], off offset:1024
	v_mul_f32_e32 v84, v112, v82
	v_mul_f32_e32 v85, v113, v82
	v_mul_f32_e32 v86, v114, v82
	v_mul_f32_e32 v87, v115, v82
	v_mul_f32_e32 v84, v194, v84
	v_mul_f32_e32 v85, v195, v85
	v_mul_f32_e32 v86, v196, v86
	v_mul_f32_e32 v87, v197, v87
	v_fma_f32 v84, v226, v84, v12
	v_fma_f32 v85, v227, v85, v13
	v_fma_f32 v86, v228, v86, v14
	v_fma_f32 v87, v229, v87, v15
	v_bfe_u32 v88, v84, 16, 1
	v_bfe_u32 v89, v85, 16, 1
	v_bfe_u32 v96, v86, 16, 1
	v_bfe_u32 v97, v87, 16, 1
	v_add3_u32 v84, v84, v88, s3
	v_add3_u32 v85, v85, v89, s3
	v_add3_u32 v86, v86, v96, s3
; __device__ __forceinline__ unsigned pk2(float lo, float hi) { return f2bf(lo) | (f2bf(hi) << 16); }
; __device__ __forceinline__ void norm_rows(const float* X, const float* nw, const float* md, u16* H, int row0, int nrows, int wave, int lane) {
;     for (int row = row0 + wave; row < row0 + nrows; row += 8) {
;         const float4* xr = (const float4*)(X + (size_t)row * DM) + lane; float4 v[8]; float ss = 0.f;
; #pragma unroll
;         for (int j = 0; j < 8; ++j) { v[j] = xr[64 * j]; ss += v[j].x * v[j].x + v[j].y * v[j].y + v[j].z * v[j].z + v[j].w * v[j].w; }
;         const float r = rsqrtf(wave_sum(ss) * (1.f / DM) + EPS);
;         uint2* hp = (uint2*)(H + (size_t)row * DM) + lane;
; #pragma unroll
;         for (int j = 0; j < 8; ++j) { const int col = 4 * (lane + 64 * j); const float4 w4 = *(const float4*)(nw + col), sc = *(const float4*)(md + 2048 + col), sh = *(const float4*)(md + col);
;             uint2 o; o.x = pk2(v[j].x * r * w4.x * (1.f + sc.x) + sh.x, v[j].y * r * w4.y * (1.f + sc.y) + sh.y);
;             o.y = pk2(v[j].z * r * w4.z * (1.f + sc.z) + sh.z, v[j].w * r * w4.w * (1.f + sc.w) + sh.w); hp[64 * j] = o; } }
	v_add3_u32 v87, v87, v97, s3
	v_perm_b32 v248, v85, v84, s101
	v_perm_b32 v249, v87, v86, s101
	global_store_dwordx2 v[78:79], v[248:249], off offset:1536
	v_mul_f32_e32 v84, v116, v82
	v_mul_f32_e32 v85, v117, v82
	v_mul_f32_e32 v86, v118, v82
	v_mul_f32_e32 v87, v119, v82
	v_mul_f32_e32 v84, v198, v84
	v_mul_f32_e32 v85, v199, v85
	v_mul_f32_e32 v86, v200, v86
	v_mul_f32_e32 v87, v201, v87
	v_fma_f32 v84, v230, v84, v16
	v_fma_f32 v85, v231, v85, v17
	v_fma_f32 v86, v232, v86, v18
	v_fma_f32 v87, v233, v87, v19
	v_bfe_u32 v88, v84, 16, 1
	v_bfe_u32 v89, v85, 16, 1
	v_bfe_u32 v96, v86, 16, 1
	v_bfe_u32 v97, v87, 16, 1
	v_add3_u32 v84, v84, v88, s3
	v_add3_u32 v85, v85, v89, s3
	v_add3_u32 v86, v86, v96, s3
	v_add3_u32 v87, v87, v97, s3
	v_perm_b32 v98, v85, v84, s101
	v_perm_b32 v99, v87, v86, s101
	global_store_dwordx2 v[78:79], v[98:99], off offset:2048
	v_mul_f32_e32 v84, v120, v82
	v_mul_f32_e32 v85, v121, v82
	v_mul_f32_e32 v86, v122, v82
	v_mul_f32_e32 v87, v123, v82
	v_mul_f32_e32 v84, v202, v84
	v_mul_f32_e32 v85, v203, v85
	v_mul_f32_e32 v86, v204, v86
	v_mul_f32_e32 v87, v205, v87
	v_fma_f32 v84, v234, v84, v20
	v_fma_f32 v85, v235, v85, v21
	v_fma_f32 v86, v236, v86, v22
	v_fma_f32 v87, v237, v87, v23
	v_bfe_u32 v88, v84, 16, 1
	v_bfe_u32 v89, v85, 16, 1
	v_bfe_u32 v96, v86, 16, 1
	v_bfe_u32 v97, v87, 16, 1
	v_add3_u32 v84, v84, v88, s3
	v_add3_u32 v85, v85, v89, s3
	v_add3_u32 v86, v86, v96, s3
	v_add3_u32 v87, v87, v97, s3
	v_perm_b32 v248, v85, v84, s101
	v_perm_b32 v249, v87, v86, s101
	global_store_dwordx2 v[78:79], v[248:249], off offset:2560
	v_mul_f32_e32 v84, v124, v82
	v_mul_f32_e32 v85, v125, v82
	v_mul_f32_e32 v86, v126, v82
	v_mul_f32_e32 v87, v127, v82
	v_mul_f32_e32 v84, v206, v84
	v_mul_f32_e32 v85, v207, v85
	v_mul_f32_e32 v86, v208, v86
	v_mul_f32_e32 v87, v209, v87
	v_fma_f32 v84, v238, v84, v66
	v_fma_f32 v85, v239, v85, v67
	v_fma_f32 v86, v240, v86, v68
	v_fma_f32 v87, v241, v87, v69
	v_bfe_u32 v88, v84, 16, 1
	v_bfe_u32 v89, v85, 16, 1
	v_bfe_u32 v96, v86, 16, 1
	v_bfe_u32 v97, v87, 16, 1
	v_add3_u32 v84, v84, v88, s3
	v_add3_u32 v85, v85, v89, s3
	v_add3_u32 v86, v86, v96, s3
	v_add3_u32 v87, v87, v97, s3
	v_perm_b32 v98, v85, v84, s101
	v_perm_b32 v99, v87, v86, s101
	global_store_dwordx2 v[78:79], v[98:99], off offset:3072
	v_mul_f32_e32 v84, v128, v82
	v_mul_f32_e32 v85, v129, v82
	v_mul_f32_e32 v86, v130, v82
	v_mul_f32_e32 v87, v131, v82
	v_mul_f32_e32 v84, v210, v84
	v_mul_f32_e32 v85, v211, v85
	v_mul_f32_e32 v86, v212, v86
	v_mul_f32_e32 v87, v213, v87
	v_fma_f32 v84, v242, v84, v70
	v_fma_f32 v85, v243, v85, v71
	v_fma_f32 v86, v244, v86, v72
	v_fma_f32 v87, v245, v87, v73
	v_bfe_u32 v88, v84, 16, 1
	v_bfe_u32 v89, v85, 16, 1
	v_bfe_u32 v96, v86, 16, 1
	v_bfe_u32 v97, v87, 16, 1
	v_add3_u32 v84, v84, v88, s3
	v_add3_u32 v85, v85, v89, s3
	v_add3_u32 v86, v86, v96, s3
	v_add3_u32 v87, v87, v97, s3
	v_perm_b32 v248, v85, v84, s101
	v_perm_b32 v249, v87, v86, s101
	global_store_dwordx2 v[78:79], v[248:249], off offset:3584
	v_lshl_add_u64 v[78:79], s[46:47], 0, v[62:63]
	v_add_co_u32_e32 v78, vcc, s13, v78
	s_nop 1
	v_addc_co_u32_e32 v79, vcc, 0, v79, vcc
	v_lshl_add_u64 v[60:61], v[60:61], 0, s[16:17]
	v_lshl_add_u64 v[62:63], v[62:63], 0, s[18:19]
	v_lshl_add_u64 v[74:75], s[46:47], 0, v[60:61]
	v_add_co_u32_e32 v76, vcc, s12, v74
	s_nop 1
	v_addc_co_u32_e32 v77, vcc, 0, v75, vcc
	v_add_co_u32_e32 v74, vcc, 0xa000000, v74
	s_nop 1
	v_addc_co_u32_e32 v75, vcc, 0, v75, vcc
	global_load_dwordx4 v[100:103], v[74:75], off
	global_load_dwordx4 v[104:107], v[74:75], off offset:1024
	global_load_dwordx4 v[108:111], v[74:75], off offset:2048
	global_load_dwordx4 v[112:115], v[74:75], off offset:3072
	global_load_dwordx4 v[116:119], v[76:77], off
	global_load_dwordx4 v[120:123], v[76:77], off offset:1024
	global_load_dwordx4 v[124:127], v[76:77], off offset:2048
	global_load_dwordx4 v[128:131], v[76:77], off offset:3072
	s_waitcnt vmcnt(16)
	v_mul_f32_e32 v81, v133, v133
	v_fmac_f32_e32 v81, v132, v132
	v_fmac_f32_e32 v81, v134, v134
	v_fmac_f32_e32 v81, v135, v135
	v_mul_f32_e32 v80, v137, v137
	v_fmac_f32_e32 v80, v136, v136
	v_fmac_f32_e32 v80, v138, v138
	v_fmac_f32_e32 v80, v139, v139
	v_add_f32_e32 v81, v81, v80
	v_mul_f32_e32 v80, v141, v141
	v_fmac_f32_e32 v80, v140, v140
	v_fmac_f32_e32 v80, v142, v142
	v_fmac_f32_e32 v80, v143, v143
	v_add_f32_e32 v81, v81, v80
	v_mul_f32_e32 v80, v145, v145
	v_fmac_f32_e32 v80, v144, v144
	v_fmac_f32_e32 v80, v146, v146
	v_fmac_f32_e32 v80, v147, v147
	v_add_f32_e32 v81, v81, v80
	v_mul_f32_e32 v80, v149, v149
	v_fmac_f32_e32 v80, v148, v148
	v_fmac_f32_e32 v80, v150, v150
	v_fmac_f32_e32 v80, v151, v151
	v_add_f32_e32 v81, v81, v80
	v_mul_f32_e32 v80, v153, v153
	v_fmac_f32_e32 v80, v152, v152
	v_fmac_f32_e32 v80, v154, v154
	v_fmac_f32_e32 v80, v155, v155
	v_add_f32_e32 v81, v81, v80
	v_mul_f32_e32 v80, v157, v157
	v_fmac_f32_e32 v80, v156, v156
	v_fmac_f32_e32 v80, v158, v158
	v_fmac_f32_e32 v80, v159, v159
	v_add_f32_e32 v81, v81, v80
	v_mul_f32_e32 v80, v161, v161
	v_fmac_f32_e32 v80, v160, v160
	v_fmac_f32_e32 v80, v162, v162
	v_fmac_f32_e32 v80, v163, v163
	v_add_f32_e32 v81, v81, v80
	ds_bpermute_b32 v80, v65, v81
	s_waitcnt lgkmcnt(0)
	v_add_f32_e32 v81, v81, v80
	ds_bpermute_b32 v80, v90, v81
	s_waitcnt lgkmcnt(0)
	v_add_f32_e32 v81, v81, v80
	ds_bpermute_b32 v80, v91, v81
	s_waitcnt lgkmcnt(0)
	v_add_f32_e32 v81, v81, v80
	ds_bpermute_b32 v80, v92, v81
	s_waitcnt lgkmcnt(0)
	v_add_f32_e32 v81, v81, v80
	ds_bpermute_b32 v80, v93, v81
	s_waitcnt lgkmcnt(0)
	v_add_f32_e32 v81, v81, v80
	ds_bpermute_b32 v80, v94, v81
	s_waitcnt lgkmcnt(0)
; __device__ __forceinline__ unsigned pk2(float lo, float hi) { return f2bf(lo) | (f2bf(hi) << 16); }
; __device__ __forceinline__ void norm_rows(const float* X, const float* nw, const float* md, u16* H, int row0, int nrows, int wave, int lane) {
;     for (int row = row0 + wave; row < row0 + nrows; row += 8) {
;         const float4* xr = (const float4*)(X + (size_t)row * DM) + lane; float4 v[8]; float ss = 0.f;
; #pragma unroll
;         for (int j = 0; j < 8; ++j) { v[j] = xr[64 * j]; ss += v[j].x * v[j].x + v[j].y * v[j].y + v[j].z * v[j].z + v[j].w * v[j].w; }
;         const float r = rsqrtf(wave_sum(ss) * (1.f / DM) + EPS);
;         uint2* hp = (uint2*)(H + (size_t)row * DM) + lane;
; #pragma unroll
;         for (int j = 0; j < 8; ++j) { const int col = 4 * (lane + 64 * j); const float4 w4 = *(const float4*)(nw + col), sc = *(const float4*)(md + 2048 + col), sh = *(const float4*)(md + col);
;             uint2 o; o.x = pk2(v[j].x * r * w4.x * (1.f + sc.x) + sh.x, v[j].y * r * w4.y * (1.f + sc.y) + sh.y);
;             o.y = pk2(v[j].z * r * w4.z * (1.f + sc.z) + sh.z, v[j].w * r * w4.w * (1.f + sc.w) + sh.w); hp[64 * j] = o; } }
	v_add_f32_e32 v81, v81, v80
	v_fmamk_f32 v81, v81, 0x3a000000, v179
	v_cmp_gt_f32_e32 vcc, s91, v81
	v_mul_f32_e32 v80, 0x4b800000, v81
	s_nop 0
	v_cndmask_b32_e32 v81, v81, v80, vcc
	v_rsq_f32_e32 v81, v81
	s_nop 0
	v_mul_f32_e32 v80, 0x45800000, v81
	v_cndmask_b32_e32 v82, v81, v80, vcc
	v_mul_f32_e32 v84, v132, v82
	v_mul_f32_e32 v85, v133, v82
	v_mul_f32_e32 v86, v134, v82
	v_mul_f32_e32 v87, v135, v82
	v_mul_f32_e32 v84, v182, v84
	v_mul_f32_e32 v85, v183, v85
	v_mul_f32_e32 v86, v184, v86
	v_mul_f32_e32 v87, v185, v87
	v_fma_f32 v84, v214, v84, v0
	v_fma_f32 v85, v215, v85, v1
	v_fma_f32 v86, v216, v86, v2
	v_fma_f32 v87, v217, v87, v3
	v_bfe_u32 v88, v84, 16, 1
	v_bfe_u32 v89, v85, 16, 1
	v_bfe_u32 v96, v86, 16, 1
	v_bfe_u32 v97, v87, 16, 1
	v_add3_u32 v84, v84, v88, s3
	v_add3_u32 v85, v85, v89, s3
	v_add3_u32 v86, v86, v96, s3
	v_add3_u32 v87, v87, v97, s3
	v_perm_b32 v98, v85, v84, s101
	v_perm_b32 v99, v87, v86, s101
	global_store_dwordx2 v[78:79], v[98:99], off
	v_mul_f32_e32 v84, v136, v82
	v_mul_f32_e32 v85, v137, v82
	v_mul_f32_e32 v86, v138, v82
	v_mul_f32_e32 v87, v139, v82
	v_mul_f32_e32 v84, v186, v84
	v_mul_f32_e32 v85, v187, v85
	v_mul_f32_e32 v86, v188, v86
	v_mul_f32_e32 v87, v189, v87
	v_fma_f32 v84, v218, v84, v4
	v_fma_f32 v85, v219, v85, v5
	v_fma_f32 v86, v220, v86, v6
	v_fma_f32 v87, v221, v87, v7
	v_bfe_u32 v88, v84, 16, 1
	v_bfe_u32 v89, v85, 16, 1
	v_bfe_u32 v96, v86, 16, 1
	v_bfe_u32 v97, v87, 16, 1
	v_add3_u32 v84, v84, v88, s3
	v_add3_u32 v85, v85, v89, s3
	v_add3_u32 v86, v86, v96, s3
	v_add3_u32 v87, v87, v97, s3
	v_perm_b32 v248, v85, v84, s101
	v_perm_b32 v249, v87, v86, s101
	global_store_dwordx2 v[78:79], v[248:249], off offset:512
	v_mul_f32_e32 v84, v140, v82
	v_mul_f32_e32 v85, v141, v82
	v_mul_f32_e32 v86, v142, v82
	v_mul_f32_e32 v87, v143, v82
	v_mul_f32_e32 v84, v190, v84
	v_mul_f32_e32 v85, v191, v85
	v_mul_f32_e32 v86, v192, v86
	v_mul_f32_e32 v87, v193, v87
	v_fma_f32 v84, v222, v84, v8
	v_fma_f32 v85, v223, v85, v9
	v_fma_f32 v86, v224, v86, v10
	v_fma_f32 v87, v225, v87, v11
	v_bfe_u32 v88, v84, 16, 1
	v_bfe_u32 v89, v85, 16, 1
	v_bfe_u32 v96, v86, 16, 1
	v_bfe_u32 v97, v87, 16, 1
	v_add3_u32 v84, v84, v88, s3
	v_add3_u32 v85, v85, v89, s3
	v_add3_u32 v86, v86, v96, s3
	v_add3_u32 v87, v87, v97, s3
	v_perm_b32 v98, v85, v84, s101
	v_perm_b32 v99, v87, v86, s101
	global_store_dwordx2 v[78:79], v[98:99], off offset:1024
	v_mul_f32_e32 v84, v144, v82
	v_mul_f32_e32 v85, v145, v82
	v_mul_f32_e32 v86, v146, v82
	v_mul_f32_e32 v87, v147, v82
	v_mul_f32_e32 v84, v194, v84
	v_mul_f32_e32 v85, v195, v85
	v_mul_f32_e32 v86, v196, v86
	v_mul_f32_e32 v87, v197, v87
	v_fma_f32 v84, v226, v84, v12
	v_fma_f32 v85, v227, v85, v13
	v_fma_f32 v86, v228, v86, v14
	v_fma_f32 v87, v229, v87, v15
	v_bfe_u32 v88, v84, 16, 1
	v_bfe_u32 v89, v85, 16, 1
	v_bfe_u32 v96, v86, 16, 1
	v_bfe_u32 v97, v87, 16, 1
	v_add3_u32 v84, v84, v88, s3
	v_add3_u32 v85, v85, v89, s3
	v_add3_u32 v86, v86, v96, s3
	v_add3_u32 v87, v87, v97, s3
	v_perm_b32 v248, v85, v84, s101
	v_perm_b32 v249, v87, v86, s101
	global_store_dwordx2 v[78:79], v[248:249], off offset:1536
	v_mul_f32_e32 v84, v148, v82
	v_mul_f32_e32 v85, v149, v82
	v_mul_f32_e32 v86, v150, v82
	v_mul_f32_e32 v87, v151, v82
	v_mul_f32_e32 v84, v198, v84
	v_mul_f32_e32 v85, v199, v85
	v_mul_f32_e32 v86, v200, v86
	v_mul_f32_e32 v87, v201, v87
	v_fma_f32 v84, v230, v84, v16
	v_fma_f32 v85, v231, v85, v17
	v_fma_f32 v86, v232, v86, v18
	v_fma_f32 v87, v233, v87, v19
	v_bfe_u32 v88, v84, 16, 1
	v_bfe_u32 v89, v85, 16, 1
	v_bfe_u32 v96, v86, 16, 1
	v_bfe_u32 v97, v87, 16, 1
	v_add3_u32 v84, v84, v88, s3
	v_add3_u32 v85, v85, v89, s3
	v_add3_u32 v86, v86, v96, s3
	v_add3_u32 v87, v87, v97, s3
	v_perm_b32 v98, v85, v84, s101
	v_perm_b32 v99, v87, v86, s101
	global_store_dwordx2 v[78:79], v[98:99], off offset:2048
	v_mul_f32_e32 v84, v152, v82
	v_mul_f32_e32 v85, v153, v82
	v_mul_f32_e32 v86, v154, v82
	v_mul_f32_e32 v87, v155, v82
	v_mul_f32_e32 v84, v202, v84
	v_mul_f32_e32 v85, v203, v85
	v_mul_f32_e32 v86, v204, v86
	v_mul_f32_e32 v87, v205, v87
	v_fma_f32 v84, v234, v84, v20
	v_fma_f32 v85, v235, v85, v21
	v_fma_f32 v86, v236, v86, v22
	v_fma_f32 v87, v237, v87, v23
	v_bfe_u32 v88, v84, 16, 1
	v_bfe_u32 v89, v85, 16, 1
	v_bfe_u32 v96, v86, 16, 1
	v_bfe_u32 v97, v87, 16, 1
	v_add3_u32 v84, v84, v88, s3
	v_add3_u32 v85, v85, v89, s3
	v_add3_u32 v86, v86, v96, s3
	v_add3_u32 v87, v87, v97, s3
	v_perm_b32 v248, v85, v84, s101
	v_perm_b32 v249, v87, v86, s101
	global_store_dwordx2 v[78:79], v[248:249], off offset:2560
	v_mul_f32_e32 v84, v156, v82
	v_mul_f32_e32 v85, v157, v82
	v_mul_f32_e32 v86, v158, v82
	v_mul_f32_e32 v87, v159, v82
	v_mul_f32_e32 v84, v206, v84
	v_mul_f32_e32 v85, v207, v85
	v_mul_f32_e32 v86, v208, v86
	v_mul_f32_e32 v87, v209, v87
	v_fma_f32 v84, v238, v84, v66
	v_fma_f32 v85, v239, v85, v67
	v_fma_f32 v86, v240, v86, v68
	v_fma_f32 v87, v241, v87, v69
	v_bfe_u32 v88, v84, 16, 1
	v_bfe_u32 v89, v85, 16, 1
	v_bfe_u32 v96, v86, 16, 1
	v_bfe_u32 v97, v87, 16, 1
	v_add3_u32 v84, v84, v88, s3
	v_add3_u32 v85, v85, v89, s3
	v_add3_u32 v86, v86, v96, s3
	v_add3_u32 v87, v87, v97, s3
	v_perm_b32 v98, v85, v84, s101
	v_perm_b32 v99, v87, v86, s101
	global_store_dwordx2 v[78:79], v[98:99], off offset:3072
	v_mul_f32_e32 v84, v160, v82
	v_mul_f32_e32 v85, v161, v82
	v_mul_f32_e32 v86, v162, v82
	v_mul_f32_e32 v87, v163, v82
	v_mul_f32_e32 v84, v210, v84
	v_mul_f32_e32 v85, v211, v85
	v_mul_f32_e32 v86, v212, v86
	v_mul_f32_e32 v87, v213, v87
	v_fma_f32 v84, v242, v84, v70
	v_fma_f32 v85, v243, v85, v71
	v_fma_f32 v86, v244, v86, v72
	v_fma_f32 v87, v245, v87, v73
	v_bfe_u32 v88, v84, 16, 1
	v_bfe_u32 v89, v85, 16, 1
	v_bfe_u32 v96, v86, 16, 1
	v_bfe_u32 v97, v87, 16, 1
	v_add3_u32 v84, v84, v88, s3
	v_add3_u32 v85, v85, v89, s3
	v_add3_u32 v86, v86, v96, s3
	v_add3_u32 v87, v87, v97, s3
	v_perm_b32 v248, v85, v84, s101
	v_perm_b32 v249, v87, v86, s101
	global_store_dwordx2 v[78:79], v[248:249], off offset:3584
	v_lshl_add_u64 v[78:79], s[46:47], 0, v[62:63]
	v_add_co_u32_e32 v78, vcc, s13, v78
	s_nop 1
	v_addc_co_u32_e32 v79, vcc, 0, v79, vcc
	v_lshl_add_u64 v[60:61], v[60:61], 0, s[16:17]
	v_lshl_add_u64 v[62:63], v[62:63], 0, s[18:19]
	v_lshl_add_u64 v[74:75], s[46:47], 0, v[60:61]
	v_add_co_u32_e32 v76, vcc, s12, v74
	s_nop 1
	v_addc_co_u32_e32 v77, vcc, 0, v75, vcc
	v_add_co_u32_e32 v74, vcc, 0xa000000, v74
	s_nop 1
	v_addc_co_u32_e32 v75, vcc, 0, v75, vcc
	global_load_dwordx4 v[132:135], v[74:75], off
	global_load_dwordx4 v[136:139], v[74:75], off offset:1024
	global_load_dwordx4 v[140:143], v[74:75], off offset:2048
	global_load_dwordx4 v[144:147], v[74:75], off offset:3072
	global_load_dwordx4 v[148:151], v[76:77], off
	global_load_dwordx4 v[152:155], v[76:77], off offset:1024
	global_load_dwordx4 v[156:159], v[76:77], off offset:2048
	global_load_dwordx4 v[160:163], v[76:77], off offset:3072
	s_waitcnt vmcnt(16)
; __device__ __forceinline__ unsigned pk2(float lo, float hi) { return f2bf(lo) | (f2bf(hi) << 16); }
; __device__ __forceinline__ void norm_rows(const float* X, const float* nw, const float* md, u16* H, int row0, int nrows, int wave, int lane) {
;     for (int row = row0 + wave; row < row0 + nrows; row += 8) {
;         const float4* xr = (const float4*)(X + (size_t)row * DM) + lane; float4 v[8]; float ss = 0.f;
; #pragma unroll
;         for (int j = 0; j < 8; ++j) { v[j] = xr[64 * j]; ss += v[j].x * v[j].x + v[j].y * v[j].y + v[j].z * v[j].z + v[j].w * v[j].w; }
;         const float r = rsqrtf(wave_sum(ss) * (1.f / DM) + EPS);
;         uint2* hp = (uint2*)(H + (size_t)row * DM) + lane;
; #pragma unroll
;         for (int j = 0; j < 8; ++j) { const int col = 4 * (lane + 64 * j); const float4 w4 = *(const float4*)(nw + col), sc = *(const float4*)(md + 2048 + col), sh = *(const float4*)(md + col);
;             uint2 o; o.x = pk2(v[j].x * r * w4.x * (1.f + sc.x) + sh.x, v[j].y * r * w4.y * (1.f + sc.y) + sh.y);
;             o.y = pk2(v[j].z * r * w4.z * (1.f + sc.z) + sh.z, v[j].w * r * w4.w * (1.f + sc.w) + sh.w); hp[64 * j] = o; } }
	v_mul_f32_e32 v81, v101, v101
	v_fmac_f32_e32 v81, v100, v100
	v_fmac_f32_e32 v81, v102, v102
	v_fmac_f32_e32 v81, v103, v103
	v_mul_f32_e32 v80, v105, v105
	v_fmac_f32_e32 v80, v104, v104
	v_fmac_f32_e32 v80, v106, v106
	v_fmac_f32_e32 v80, v107, v107
	v_add_f32_e32 v81, v81, v80
	v_mul_f32_e32 v80, v109, v109
	v_fmac_f32_e32 v80, v108, v108
	v_fmac_f32_e32 v80, v110, v110
	v_fmac_f32_e32 v80, v111, v111
	v_add_f32_e32 v81, v81, v80
	v_mul_f32_e32 v80, v113, v113
	v_fmac_f32_e32 v80, v112, v112
	v_fmac_f32_e32 v80, v114, v114
	v_fmac_f32_e32 v80, v115, v115
	v_add_f32_e32 v81, v81, v80
	v_mul_f32_e32 v80, v117, v117
	v_fmac_f32_e32 v80, v116, v116
	v_fmac_f32_e32 v80, v118, v118
	v_fmac_f32_e32 v80, v119, v119
	v_add_f32_e32 v81, v81, v80
	v_mul_f32_e32 v80, v121, v121
	v_fmac_f32_e32 v80, v120, v120
	v_fmac_f32_e32 v80, v122, v122
	v_fmac_f32_e32 v80, v123, v123
	v_add_f32_e32 v81, v81, v80
	v_mul_f32_e32 v80, v125, v125
	v_fmac_f32_e32 v80, v124, v124
	v_fmac_f32_e32 v80, v126, v126
	v_fmac_f32_e32 v80, v127, v127
	v_add_f32_e32 v81, v81, v80
	v_mul_f32_e32 v80, v129, v129
	v_fmac_f32_e32 v80, v128, v128
	v_fmac_f32_e32 v80, v130, v130
	v_fmac_f32_e32 v80, v131, v131
	v_add_f32_e32 v81, v81, v80
	ds_bpermute_b32 v80, v65, v81
	s_waitcnt lgkmcnt(0)
	v_add_f32_e32 v81, v81, v80
	ds_bpermute_b32 v80, v90, v81
	s_waitcnt lgkmcnt(0)
	v_add_f32_e32 v81, v81, v80
	ds_bpermute_b32 v80, v91, v81
	s_waitcnt lgkmcnt(0)
	v_add_f32_e32 v81, v81, v80
	ds_bpermute_b32 v80, v92, v81
	s_waitcnt lgkmcnt(0)
	v_add_f32_e32 v81, v81, v80
	ds_bpermute_b32 v80, v93, v81
	s_waitcnt lgkmcnt(0)
	v_add_f32_e32 v81, v81, v80
	ds_bpermute_b32 v80, v94, v81
	s_waitcnt lgkmcnt(0)
	v_add_f32_e32 v81, v81, v80
	v_fmamk_f32 v81, v81, 0x3a000000, v179
	v_cmp_gt_f32_e32 vcc, s91, v81
	v_mul_f32_e32 v80, 0x4b800000, v81
	s_nop 0
	v_cndmask_b32_e32 v81, v81, v80, vcc
	v_rsq_f32_e32 v81, v81
	s_nop 0
	v_mul_f32_e32 v80, 0x45800000, v81
	v_cndmask_b32_e32 v82, v81, v80, vcc
	v_mul_f32_e32 v84, v100, v82
	v_mul_f32_e32 v85, v101, v82
	v_mul_f32_e32 v86, v102, v82
	v_mul_f32_e32 v87, v103, v82
	v_mul_f32_e32 v84, v182, v84
	v_mul_f32_e32 v85, v183, v85
	v_mul_f32_e32 v86, v184, v86
	v_mul_f32_e32 v87, v185, v87
	v_fma_f32 v84, v214, v84, v0
	v_fma_f32 v85, v215, v85, v1
	v_fma_f32 v86, v216, v86, v2
	v_fma_f32 v87, v217, v87, v3
	v_bfe_u32 v88, v84, 16, 1
	v_bfe_u32 v89, v85, 16, 1
	v_bfe_u32 v96, v86, 16, 1
	v_bfe_u32 v97, v87, 16, 1
	v_add3_u32 v84, v84, v88, s3
	v_add3_u32 v85, v85, v89, s3
	v_add3_u32 v86, v86, v96, s3
	v_add3_u32 v87, v87, v97, s3
	v_perm_b32 v98, v85, v84, s101
	v_perm_b32 v99, v87, v86, s101
	global_store_dwordx2 v[78:79], v[98:99], off
	v_mul_f32_e32 v84, v104, v82
	v_mul_f32_e32 v85, v105, v82
	v_mul_f32_e32 v86, v106, v82
	v_mul_f32_e32 v87, v107, v82
	v_mul_f32_e32 v84, v186, v84
	v_mul_f32_e32 v85, v187, v85
	v_mul_f32_e32 v86, v188, v86
	v_mul_f32_e32 v87, v189, v87
	v_fma_f32 v84, v218, v84, v4
	v_fma_f32 v85, v219, v85, v5
	v_fma_f32 v86, v220, v86, v6
	v_fma_f32 v87, v221, v87, v7
	v_bfe_u32 v88, v84, 16, 1
	v_bfe_u32 v89, v85, 16, 1
	v_bfe_u32 v96, v86, 16, 1
	v_bfe_u32 v97, v87, 16, 1
	v_add3_u32 v84, v84, v88, s3
	v_add3_u32 v85, v85, v89, s3
	v_add3_u32 v86, v86, v96, s3
	v_add3_u32 v87, v87, v97, s3
	v_perm_b32 v248, v85, v84, s101
	v_perm_b32 v249, v87, v86, s101
	global_store_dwordx2 v[78:79], v[248:249], off offset:512
	v_mul_f32_e32 v84, v108, v82
	v_mul_f32_e32 v85, v109, v82
	v_mul_f32_e32 v86, v110, v82
	v_mul_f32_e32 v87, v111, v82
	v_mul_f32_e32 v84, v190, v84
	v_mul_f32_e32 v85, v191, v85
	v_mul_f32_e32 v86, v192, v86
	v_mul_f32_e32 v87, v193, v87
	v_fma_f32 v84, v222, v84, v8
	v_fma_f32 v85, v223, v85, v9
	v_fma_f32 v86, v224, v86, v10
	v_fma_f32 v87, v225, v87, v11
	v_bfe_u32 v88, v84, 16, 1
	v_bfe_u32 v89, v85, 16, 1
	v_bfe_u32 v96, v86, 16, 1
	v_bfe_u32 v97, v87, 16, 1
	v_add3_u32 v84, v84, v88, s3
	v_add3_u32 v85, v85, v89, s3
	v_add3_u32 v86, v86, v96, s3
	v_add3_u32 v87, v87, v97, s3
	v_perm_b32 v98, v85, v84, s101
	v_perm_b32 v99, v87, v86, s101
	global_store_dwordx2 v[78:79], v[98:99], off offset:1024
	v_mul_f32_e32 v84, v112, v82
	v_mul_f32_e32 v85, v113, v82
	v_mul_f32_e32 v86, v114, v82
	v_mul_f32_e32 v87, v115, v82
	v_mul_f32_e32 v84, v194, v84
	v_mul_f32_e32 v85, v195, v85
	v_mul_f32_e32 v86, v196, v86
	v_mul_f32_e32 v87, v197, v87
	v_fma_f32 v84, v226, v84, v12
	v_fma_f32 v85, v227, v85, v13
	v_fma_f32 v86, v228, v86, v14
	v_fma_f32 v87, v229, v87, v15
	v_bfe_u32 v88, v84, 16, 1
	v_bfe_u32 v89, v85, 16, 1
	v_bfe_u32 v96, v86, 16, 1
	v_bfe_u32 v97, v87, 16, 1
	v_add3_u32 v84, v84, v88, s3
	v_add3_u32 v85, v85, v89, s3
	v_add3_u32 v86, v86, v96, s3
	v_add3_u32 v87, v87, v97, s3
	v_perm_b32 v248, v85, v84, s101
	v_perm_b32 v249, v87, v86, s101
	global_store_dwordx2 v[78:79], v[248:249], off offset:1536
	v_mul_f32_e32 v84, v116, v82
	v_mul_f32_e32 v85, v117, v82
	v_mul_f32_e32 v86, v118, v82
	v_mul_f32_e32 v87, v119, v82
	v_mul_f32_e32 v84, v198, v84
	v_mul_f32_e32 v85, v199, v85
	v_mul_f32_e32 v86, v200, v86
	v_mul_f32_e32 v87, v201, v87
	v_fma_f32 v84, v230, v84, v16
	v_fma_f32 v85, v231, v85, v17
	v_fma_f32 v86, v232, v86, v18
	v_fma_f32 v87, v233, v87, v19
	v_bfe_u32 v88, v84, 16, 1
	v_bfe_u32 v89, v85, 16, 1
	v_bfe_u32 v96, v86, 16, 1
	v_bfe_u32 v97, v87, 16, 1
	v_add3_u32 v84, v84, v88, s3
	v_add3_u32 v85, v85, v89, s3
	v_add3_u32 v86, v86, v96, s3
	v_add3_u32 v87, v87, v97, s3
	v_perm_b32 v98, v85, v84, s101
	v_perm_b32 v99, v87, v86, s101
	global_store_dwordx2 v[78:79], v[98:99], off offset:2048
	v_mul_f32_e32 v84, v120, v82
	v_mul_f32_e32 v85, v121, v82
	v_mul_f32_e32 v86, v122, v82
	v_mul_f32_e32 v87, v123, v82
; __device__ __forceinline__ unsigned pk2(float lo, float hi) { return f2bf(lo) | (f2bf(hi) << 16); }
; __device__ __forceinline__ void norm_rows(const float* X, const float* nw, const float* md, u16* H, int row0, int nrows, int wave, int lane) {
;     for (int row = row0 + wave; row < row0 + nrows; row += 8) {
;         const float4* xr = (const float4*)(X + (size_t)row * DM) + lane; float4 v[8]; float ss = 0.f;
; #pragma unroll
;         for (int j = 0; j < 8; ++j) { v[j] = xr[64 * j]; ss += v[j].x * v[j].x + v[j].y * v[j].y + v[j].z * v[j].z + v[j].w * v[j].w; }
;         const float r = rsqrtf(wave_sum(ss) * (1.f / DM) + EPS);
;         uint2* hp = (uint2*)(H + (size_t)row * DM) + lane;
; #pragma unroll
;         for (int j = 0; j < 8; ++j) { const int col = 4 * (lane + 64 * j); const float4 w4 = *(const float4*)(nw + col), sc = *(const float4*)(md + 2048 + col), sh = *(const float4*)(md + col);
;             uint2 o; o.x = pk2(v[j].x * r * w4.x * (1.f + sc.x) + sh.x, v[j].y * r * w4.y * (1.f + sc.y) + sh.y);
;             o.y = pk2(v[j].z * r * w4.z * (1.f + sc.z) + sh.z, v[j].w * r * w4.w * (1.f + sc.w) + sh.w); hp[64 * j] = o; } }
	v_mul_f32_e32 v84, v202, v84
	v_mul_f32_e32 v85, v203, v85
	v_mul_f32_e32 v86, v204, v86
	v_mul_f32_e32 v87, v205, v87
	v_fma_f32 v84, v234, v84, v20
	v_fma_f32 v85, v235, v85, v21
	v_fma_f32 v86, v236, v86, v22
	v_fma_f32 v87, v237, v87, v23
	v_bfe_u32 v88, v84, 16, 1
	v_bfe_u32 v89, v85, 16, 1
	v_bfe_u32 v96, v86, 16, 1
	v_bfe_u32 v97, v87, 16, 1
	v_add3_u32 v84, v84, v88, s3
	v_add3_u32 v85, v85, v89, s3
	v_add3_u32 v86, v86, v96, s3
	v_add3_u32 v87, v87, v97, s3
	v_perm_b32 v248, v85, v84, s101
	v_perm_b32 v249, v87, v86, s101
	global_store_dwordx2 v[78:79], v[248:249], off offset:2560
	v_mul_f32_e32 v84, v124, v82
	v_mul_f32_e32 v85, v125, v82
	v_mul_f32_e32 v86, v126, v82
	v_mul_f32_e32 v87, v127, v82
	v_mul_f32_e32 v84, v206, v84
	v_mul_f32_e32 v85, v207, v85
	v_mul_f32_e32 v86, v208, v86
	v_mul_f32_e32 v87, v209, v87
	v_fma_f32 v84, v238, v84, v66
	v_fma_f32 v85, v239, v85, v67
	v_fma_f32 v86, v240, v86, v68
	v_fma_f32 v87, v241, v87, v69
	v_bfe_u32 v88, v84, 16, 1
	v_bfe_u32 v89, v85, 16, 1
	v_bfe_u32 v96, v86, 16, 1
	v_bfe_u32 v97, v87, 16, 1
	v_add3_u32 v84, v84, v88, s3
	v_add3_u32 v85, v85, v89, s3
	v_add3_u32 v86, v86, v96, s3
	v_add3_u32 v87, v87, v97, s3
	v_perm_b32 v98, v85, v84, s101
	v_perm_b32 v99, v87, v86, s101
	global_store_dwordx2 v[78:79], v[98:99], off offset:3072
	v_mul_f32_e32 v84, v128, v82
	v_mul_f32_e32 v85, v129, v82
	v_mul_f32_e32 v86, v130, v82
	v_mul_f32_e32 v87, v131, v82
	v_mul_f32_e32 v84, v210, v84
	v_mul_f32_e32 v85, v211, v85
	v_mul_f32_e32 v86, v212, v86
	v_mul_f32_e32 v87, v213, v87
	v_fma_f32 v84, v242, v84, v70
	v_fma_f32 v85, v243, v85, v71
	v_fma_f32 v86, v244, v86, v72
	v_fma_f32 v87, v245, v87, v73
	v_bfe_u32 v88, v84, 16, 1
	v_bfe_u32 v89, v85, 16, 1
	v_bfe_u32 v96, v86, 16, 1
	v_bfe_u32 v97, v87, 16, 1
	v_add3_u32 v84, v84, v88, s3
	v_add3_u32 v85, v85, v89, s3
	v_add3_u32 v86, v86, v96, s3
	v_add3_u32 v87, v87, v97, s3
	v_perm_b32 v248, v85, v84, s101
	v_perm_b32 v249, v87, v86, s101
	global_store_dwordx2 v[78:79], v[248:249], off offset:3584
	v_lshl_add_u64 v[78:79], s[46:47], 0, v[62:63]
	v_add_co_u32_e32 v78, vcc, s13, v78
	s_nop 1
	v_addc_co_u32_e32 v79, vcc, 0, v79, vcc
	s_waitcnt vmcnt(8)
	v_mul_f32_e32 v81, v133, v133
	v_fmac_f32_e32 v81, v132, v132
	v_fmac_f32_e32 v81, v134, v134
	v_fmac_f32_e32 v81, v135, v135
	v_mul_f32_e32 v80, v137, v137
	v_fmac_f32_e32 v80, v136, v136
	v_fmac_f32_e32 v80, v138, v138
	v_fmac_f32_e32 v80, v139, v139
	v_add_f32_e32 v81, v81, v80
	v_mul_f32_e32 v80, v141, v141
	v_fmac_f32_e32 v80, v140, v140
	v_fmac_f32_e32 v80, v142, v142
	v_fmac_f32_e32 v80, v143, v143
	v_add_f32_e32 v81, v81, v80
	v_mul_f32_e32 v80, v145, v145
	v_fmac_f32_e32 v80, v144, v144
	v_fmac_f32_e32 v80, v146, v146
	v_fmac_f32_e32 v80, v147, v147
	v_add_f32_e32 v81, v81, v80
	v_mul_f32_e32 v80, v149, v149
	v_fmac_f32_e32 v80, v148, v148
	v_fmac_f32_e32 v80, v150, v150
	v_fmac_f32_e32 v80, v151, v151
	v_add_f32_e32 v81, v81, v80
	v_mul_f32_e32 v80, v153, v153
	v_fmac_f32_e32 v80, v152, v152
	v_fmac_f32_e32 v80, v154, v154
	v_fmac_f32_e32 v80, v155, v155
	v_add_f32_e32 v81, v81, v80
	v_mul_f32_e32 v80, v157, v157
	v_fmac_f32_e32 v80, v156, v156
	v_fmac_f32_e32 v80, v158, v158
	v_fmac_f32_e32 v80, v159, v159
	v_add_f32_e32 v81, v81, v80
	v_mul_f32_e32 v80, v161, v161
	v_fmac_f32_e32 v80, v160, v160
	v_fmac_f32_e32 v80, v162, v162
	v_fmac_f32_e32 v80, v163, v163
	v_add_f32_e32 v81, v81, v80
	ds_bpermute_b32 v80, v65, v81
	s_waitcnt lgkmcnt(0)
	v_add_f32_e32 v81, v81, v80
	ds_bpermute_b32 v80, v90, v81
	s_waitcnt lgkmcnt(0)
	v_add_f32_e32 v81, v81, v80
	ds_bpermute_b32 v80, v91, v81
	s_waitcnt lgkmcnt(0)
	v_add_f32_e32 v81, v81, v80
	ds_bpermute_b32 v80, v92, v81
	s_waitcnt lgkmcnt(0)
	v_add_f32_e32 v81, v81, v80
	ds_bpermute_b32 v80, v93, v81
	s_waitcnt lgkmcnt(0)
	v_add_f32_e32 v81, v81, v80
	ds_bpermute_b32 v80, v94, v81
	s_waitcnt lgkmcnt(0)
; __device__ __forceinline__ unsigned pk2(float lo, float hi) { return f2bf(lo) | (f2bf(hi) << 16); }
; __device__ __forceinline__ void norm_rows(const float* X, const float* nw, const float* md, u16* H, int row0, int nrows, int wave, int lane) {
;     ...
;         const float r = rsqrtf(wave_sum(ss) * (1.f / DM) + EPS);
;         uint2* hp = (uint2*)(H + (size_t)row * DM) + lane;
; #pragma unroll
;         for (int j = 0; j < 8; ++j) { const int col = 4 * (lane + 64 * j); const float4 w4 = *(const float4*)(nw + col), sc = *(const float4*)(md + 2048 + col), sh = *(const float4*)(md + col);
;             uint2 o; o.x = pk2(v[j].x * r * w4.x * (1.f + sc.x) + sh.x, v[j].y * r * w4.y * (1.f + sc.y) + sh.y);
;             o.y = pk2(v[j].z * r * w4.z * (1.f + sc.z) + sh.z, v[j].w * r * w4.w * (1.f + sc.w) + sh.w); hp[64 * j] = o; } }
	v_add_f32_e32 v81, v81, v80
	v_fmamk_f32 v81, v81, 0x3a000000, v179
	v_cmp_gt_f32_e32 vcc, s91, v81
	v_mul_f32_e32 v80, 0x4b800000, v81
	s_nop 0
	v_cndmask_b32_e32 v81, v81, v80, vcc
	v_rsq_f32_e32 v81, v81
	s_nop 0
	v_mul_f32_e32 v80, 0x45800000, v81
	v_cndmask_b32_e32 v82, v81, v80, vcc
	v_mul_f32_e32 v84, v132, v82
	v_mul_f32_e32 v85, v133, v82
	v_mul_f32_e32 v86, v134, v82
	v_mul_f32_e32 v87, v135, v82
	v_mul_f32_e32 v84, v182, v84
	v_mul_f32_e32 v85, v183, v85
	v_mul_f32_e32 v86, v184, v86
	v_mul_f32_e32 v87, v185, v87
	v_fma_f32 v84, v214, v84, v0
	v_fma_f32 v85, v215, v85, v1
	v_fma_f32 v86, v216, v86, v2
	v_fma_f32 v87, v217, v87, v3
	v_bfe_u32 v88, v84, 16, 1
	v_bfe_u32 v89, v85, 16, 1
	v_bfe_u32 v96, v86, 16, 1
	v_bfe_u32 v97, v87, 16, 1
	v_add3_u32 v84, v84, v88, s3
	v_add3_u32 v85, v85, v89, s3
	v_add3_u32 v86, v86, v96, s3
	v_add3_u32 v87, v87, v97, s3
	v_perm_b32 v98, v85, v84, s101
	v_perm_b32 v99, v87, v86, s101
	global_store_dwordx2 v[78:79], v[98:99], off
	v_mul_f32_e32 v84, v136, v82
	v_mul_f32_e32 v85, v137, v82
	v_mul_f32_e32 v86, v138, v82
	v_mul_f32_e32 v87, v139, v82
	v_mul_f32_e32 v84, v186, v84
	v_mul_f32_e32 v85, v187, v85
	v_mul_f32_e32 v86, v188, v86
	v_mul_f32_e32 v87, v189, v87
	v_fma_f32 v84, v218, v84, v4
	v_fma_f32 v85, v219, v85, v5
	v_fma_f32 v86, v220, v86, v6
	v_fma_f32 v87, v221, v87, v7
	v_bfe_u32 v88, v84, 16, 1
	v_bfe_u32 v89, v85, 16, 1
	v_bfe_u32 v96, v86, 16, 1
	v_bfe_u32 v97, v87, 16, 1
	v_add3_u32 v84, v84, v88, s3
	v_add3_u32 v85, v85, v89, s3
	v_add3_u32 v86, v86, v96, s3
	v_add3_u32 v87, v87, v97, s3
	v_perm_b32 v248, v85, v84, s101
	v_perm_b32 v249, v87, v86, s101
	global_store_dwordx2 v[78:79], v[248:249], off offset:512
	v_mul_f32_e32 v84, v140, v82
	v_mul_f32_e32 v85, v141, v82
	v_mul_f32_e32 v86, v142, v82
	v_mul_f32_e32 v87, v143, v82
	v_mul_f32_e32 v84, v190, v84
	v_mul_f32_e32 v85, v191, v85
	v_mul_f32_e32 v86, v192, v86
	v_mul_f32_e32 v87, v193, v87
	v_fma_f32 v84, v222, v84, v8
	v_fma_f32 v85, v223, v85, v9
	v_fma_f32 v86, v224, v86, v10
	v_fma_f32 v87, v225, v87, v11
	v_bfe_u32 v88, v84, 16, 1
	v_bfe_u32 v89, v85, 16, 1
	v_bfe_u32 v96, v86, 16, 1
	v_bfe_u32 v97, v87, 16, 1
	v_add3_u32 v84, v84, v88, s3
	v_add3_u32 v85, v85, v89, s3
	v_add3_u32 v86, v86, v96, s3
	v_add3_u32 v87, v87, v97, s3
	v_perm_b32 v98, v85, v84, s101
	v_perm_b32 v99, v87, v86, s101
	global_store_dwordx2 v[78:79], v[98:99], off offset:1024
	v_mul_f32_e32 v84, v144, v82
	v_mul_f32_e32 v85, v145, v82
	v_mul_f32_e32 v86, v146, v82
	v_mul_f32_e32 v87, v147, v82
	v_mul_f32_e32 v84, v194, v84
	v_mul_f32_e32 v85, v195, v85
	v_mul_f32_e32 v86, v196, v86
	v_mul_f32_e32 v87, v197, v87
	v_fma_f32 v84, v226, v84, v12
	v_fma_f32 v85, v227, v85, v13
	v_fma_f32 v86, v228, v86, v14
	v_fma_f32 v87, v229, v87, v15
	v_bfe_u32 v88, v84, 16, 1
	v_bfe_u32 v89, v85, 16, 1
	v_bfe_u32 v96, v86, 16, 1
	v_bfe_u32 v97, v87, 16, 1
	v_add3_u32 v84, v84, v88, s3
	v_add3_u32 v85, v85, v89, s3
	v_add3_u32 v86, v86, v96, s3
	v_add3_u32 v87, v87, v97, s3
	v_perm_b32 v248, v85, v84, s101
	v_perm_b32 v249, v87, v86, s101
	global_store_dwordx2 v[78:79], v[248:249], off offset:1536
	v_mul_f32_e32 v84, v148, v82
	v_mul_f32_e32 v85, v149, v82
	v_mul_f32_e32 v86, v150, v82
	v_mul_f32_e32 v87, v151, v82
	v_mul_f32_e32 v84, v198, v84
	v_mul_f32_e32 v85, v199, v85
	v_mul_f32_e32 v86, v200, v86
	v_mul_f32_e32 v87, v201, v87
	v_fma_f32 v84, v230, v84, v16
	v_fma_f32 v85, v231, v85, v17
	v_fma_f32 v86, v232, v86, v18
	v_fma_f32 v87, v233, v87, v19
	v_bfe_u32 v88, v84, 16, 1
	v_bfe_u32 v89, v85, 16, 1
	v_bfe_u32 v96, v86, 16, 1
	v_bfe_u32 v97, v87, 16, 1
	v_add3_u32 v84, v84, v88, s3
	v_add3_u32 v85, v85, v89, s3
	v_add3_u32 v86, v86, v96, s3
	v_add3_u32 v87, v87, v97, s3
	v_perm_b32 v98, v85, v84, s101
	v_perm_b32 v99, v87, v86, s101
	global_store_dwordx2 v[78:79], v[98:99], off offset:2048
	v_mul_f32_e32 v84, v152, v82
	v_mul_f32_e32 v85, v153, v82
	v_mul_f32_e32 v86, v154, v82
	v_mul_f32_e32 v87, v155, v82
	v_mul_f32_e32 v84, v202, v84
	v_mul_f32_e32 v85, v203, v85
	v_mul_f32_e32 v86, v204, v86
	v_mul_f32_e32 v87, v205, v87
	v_fma_f32 v84, v234, v84, v20
	v_fma_f32 v85, v235, v85, v21
	v_fma_f32 v86, v236, v86, v22
	v_fma_f32 v87, v237, v87, v23
	v_bfe_u32 v88, v84, 16, 1
	v_bfe_u32 v89, v85, 16, 1
	v_bfe_u32 v96, v86, 16, 1
	v_bfe_u32 v97, v87, 16, 1
	v_add3_u32 v84, v84, v88, s3
	v_add3_u32 v85, v85, v89, s3
	v_add3_u32 v86, v86, v96, s3
	v_add3_u32 v87, v87, v97, s3
	v_perm_b32 v248, v85, v84, s101
	v_perm_b32 v249, v87, v86, s101
	global_store_dwordx2 v[78:79], v[248:249], off offset:2560
	v_mul_f32_e32 v84, v156, v82
	v_mul_f32_e32 v85, v157, v82
	v_mul_f32_e32 v86, v158, v82
	v_mul_f32_e32 v87, v159, v82
	v_mul_f32_e32 v84, v206, v84
	v_mul_f32_e32 v85, v207, v85
	v_mul_f32_e32 v86, v208, v86
	v_mul_f32_e32 v87, v209, v87
	v_fma_f32 v84, v238, v84, v66
	v_fma_f32 v85, v239, v85, v67
	v_fma_f32 v86, v240, v86, v68
	v_fma_f32 v87, v241, v87, v69
	v_bfe_u32 v88, v84, 16, 1
	v_bfe_u32 v89, v85, 16, 1
	v_bfe_u32 v96, v86, 16, 1
	v_bfe_u32 v97, v87, 16, 1
	v_add3_u32 v84, v84, v88, s3
	v_add3_u32 v85, v85, v89, s3
	v_add3_u32 v86, v86, v96, s3
	v_add3_u32 v87, v87, v97, s3
	v_perm_b32 v98, v85, v84, s101
	v_perm_b32 v99, v87, v86, s101
	global_store_dwordx2 v[78:79], v[98:99], off offset:3072
	v_mul_f32_e32 v84, v160, v82
	v_mul_f32_e32 v85, v161, v82
	v_mul_f32_e32 v86, v162, v82
	v_mul_f32_e32 v87, v163, v82
	v_mul_f32_e32 v84, v210, v84
	v_mul_f32_e32 v85, v211, v85
	v_mul_f32_e32 v86, v212, v86
	v_mul_f32_e32 v87, v213, v87
	v_fma_f32 v84, v242, v84, v70
	v_fma_f32 v85, v243, v85, v71
	v_fma_f32 v86, v244, v86, v72
	v_fma_f32 v87, v245, v87, v73
	v_bfe_u32 v88, v84, 16, 1
	v_bfe_u32 v89, v85, 16, 1
	v_bfe_u32 v96, v86, 16, 1
	v_bfe_u32 v97, v87, 16, 1
	v_add3_u32 v84, v84, v88, s3
	v_add3_u32 v85, v85, v89, s3
	v_add3_u32 v86, v86, v96, s3
	v_add3_u32 v87, v87, v97, s3
	v_perm_b32 v248, v85, v84, s101
	v_perm_b32 v249, v87, v86, s101
	global_store_dwordx2 v[78:79], v[248:249], off offset:3584
